# RG-LRU depthwise conv: all taps of two row groups loaded together (one wait) instead of a wait per tap; both instances
# speedup vs baseline: 1.0510x; 1.0149x over previous
.LBB0_1034:
	v_add_u32_e32 v216, s4, v177
	v_mov_b32_e32 v217, v216
	v_add_u32_e32 v227, 32, v216
	v_add_u32_e32 v244, s4, v92
	v_add_u32_e32 v244, -1, v244
	v_ashrrev_i32_e32 v245, 31, v244
	v_lshlrev_b64 v[244:245], 12, v[244:245]
	v_lshl_add_u64 v[208:209], v[76:77], 0, v[244:245]
	s_mov_b32 s0, 0x2000
	s_mov_b32 s1, 0
	v_lshl_add_u64 v[210:211], v[208:209], 0, s[0:1]
	s_mov_b32 s0, 0x20000
	v_lshl_add_u64 v[212:213], v[208:209], 0, s[0:1]
	v_lshl_add_u64 v[214:215], v[210:211], 0, s[0:1]
	v_mov_b32_e32 v100, 0
	v_mov_b32_e32 v101, 0
	v_mov_b32_e32 v102, 0
	v_mov_b32_e32 v103, 0
	v_mov_b32_e32 v104, 0
	v_mov_b32_e32 v105, 0
	v_mov_b32_e32 v106, 0
	v_mov_b32_e32 v107, 0
	v_mov_b32_e32 v128, 0
	v_mov_b32_e32 v129, 0
	v_mov_b32_e32 v130, 0
	v_mov_b32_e32 v131, 0
	v_mov_b32_e32 v132, 0
	v_mov_b32_e32 v133, 0
	v_mov_b32_e32 v134, 0
	v_mov_b32_e32 v135, 0
	v_mov_b32_e32 v136, 0
	v_mov_b32_e32 v137, 0
	v_mov_b32_e32 v138, 0
	v_mov_b32_e32 v139, 0
	v_mov_b32_e32 v96, 0
	v_mov_b32_e32 v97, 0
	v_mov_b32_e32 v98, 0
	v_mov_b32_e32 v99, 0
	s_movk_i32 s1, 255
	v_cmp_lt_u32_e64 s[12:13], 1, v217
	v_cmp_lt_u32_e64 s[20:21], 0, v217
	v_cmp_gt_u32_e64 s[48:49], s1, v217
	s_mov_b64 exec, s[12:13]
	global_load_dwordx4 v[100:103], v[208:209], off offset:-4096
	s_mov_b64 exec, s[20:21]
	global_load_dwordx4 v[104:107], v[208:209], off
	s_mov_b64 exec, -1
	global_load_dwordx4 v[108:111], v[210:211], off offset:-4096
	s_mov_b64 exec, s[48:49]
	global_load_dwordx4 v[128:131], v[210:211], off
	s_mov_b64 exec, -1
	v_cmp_lt_u32_e64 s[12:13], 1, v227
	v_cmp_lt_u32_e64 s[20:21], 0, v227
	v_cmp_gt_u32_e64 s[48:49], s1, v227
	s_mov_b64 exec, s[12:13]
	global_load_dwordx4 v[132:135], v[212:213], off offset:-4096
	s_mov_b64 exec, s[20:21]
	global_load_dwordx4 v[136:139], v[212:213], off
	s_mov_b64 exec, -1
	global_load_dwordx4 v[140:143], v[214:215], off offset:-4096
	s_mov_b64 exec, s[48:49]
	global_load_dwordx4 v[96:99], v[214:215], off
	s_mov_b64 exec, -1
	s_waitcnt vmcnt(0)
	v_lshlrev_b32_e32 v236, 16, v100
	v_and_b32_e32 v237, 0xffff0000, v100
	v_pk_fma_f32 v[228:229], v[48:49], v[236:237], v[40:41]
	v_lshlrev_b32_e32 v236, 16, v101
	v_and_b32_e32 v237, 0xffff0000, v101
	v_pk_fma_f32 v[230:231], v[50:51], v[236:237], v[42:43]
	v_lshlrev_b32_e32 v236, 16, v102
	v_and_b32_e32 v237, 0xffff0000, v102
	v_pk_fma_f32 v[232:233], v[44:45], v[236:237], v[36:37]
	v_lshlrev_b32_e32 v236, 16, v103
	v_and_b32_e32 v237, 0xffff0000, v103
	v_pk_fma_f32 v[234:235], v[46:47], v[236:237], v[38:39]
	v_lshlrev_b32_e32 v236, 16, v104
	v_and_b32_e32 v237, 0xffff0000, v104
	v_pk_fma_f32 v[228:229], v[68:69], v[236:237], v[228:229]
	v_lshlrev_b32_e32 v236, 16, v105
	v_and_b32_e32 v237, 0xffff0000, v105
	v_pk_fma_f32 v[230:231], v[70:71], v[236:237], v[230:231]
	v_lshlrev_b32_e32 v236, 16, v106
	v_and_b32_e32 v237, 0xffff0000, v106
	v_pk_fma_f32 v[232:233], v[52:53], v[236:237], v[232:233]
	v_lshlrev_b32_e32 v236, 16, v107
	v_and_b32_e32 v237, 0xffff0000, v107
	v_pk_fma_f32 v[234:235], v[54:55], v[236:237], v[234:235]
	v_lshlrev_b32_e32 v236, 16, v108
	v_and_b32_e32 v237, 0xffff0000, v108
	v_pk_fma_f32 v[228:229], v[60:61], v[236:237], v[228:229]
	v_lshlrev_b32_e32 v236, 16, v109
	v_and_b32_e32 v237, 0xffff0000, v109
	v_pk_fma_f32 v[230:231], v[62:63], v[236:237], v[230:231]
	v_lshlrev_b32_e32 v236, 16, v110
	v_and_b32_e32 v237, 0xffff0000, v110
	v_pk_fma_f32 v[232:233], v[56:57], v[236:237], v[232:233]
	v_lshlrev_b32_e32 v236, 16, v111
	v_and_b32_e32 v237, 0xffff0000, v111
	v_pk_fma_f32 v[234:235], v[58:59], v[236:237], v[234:235]
	v_lshlrev_b32_e32 v236, 16, v128
	v_and_b32_e32 v237, 0xffff0000, v128
	v_pk_fma_f32 v[228:229], v[64:65], v[236:237], v[228:229]
	v_lshlrev_b32_e32 v236, 16, v129
	v_and_b32_e32 v237, 0xffff0000, v129
	v_pk_fma_f32 v[230:231], v[66:67], v[236:237], v[230:231]
	v_lshlrev_b32_e32 v236, 16, v130
	v_and_b32_e32 v237, 0xffff0000, v130
	v_pk_fma_f32 v[232:233], v[72:73], v[236:237], v[232:233]
	v_lshlrev_b32_e32 v236, 16, v131
	v_and_b32_e32 v237, 0xffff0000, v131
	v_pk_fma_f32 v[234:235], v[74:75], v[236:237], v[234:235]
	v_cvt_pk_bf16_f32 v240, v228, v229
	v_cvt_pk_bf16_f32 v241, v230, v231
	v_cvt_pk_bf16_f32 v242, v232, v233
	v_cvt_pk_bf16_f32 v243, v234, v235
	ds_write_b128 v93, v[240:243]
	v_lshlrev_b32_e32 v236, 16, v132
	v_and_b32_e32 v237, 0xffff0000, v132
	v_pk_fma_f32 v[228:229], v[48:49], v[236:237], v[40:41]
	v_lshlrev_b32_e32 v236, 16, v133
	v_and_b32_e32 v237, 0xffff0000, v133
	v_pk_fma_f32 v[230:231], v[50:51], v[236:237], v[42:43]
	v_lshlrev_b32_e32 v236, 16, v134
	v_and_b32_e32 v237, 0xffff0000, v134
	v_pk_fma_f32 v[232:233], v[44:45], v[236:237], v[36:37]
	v_lshlrev_b32_e32 v236, 16, v135
	v_and_b32_e32 v237, 0xffff0000, v135
	v_pk_fma_f32 v[234:235], v[46:47], v[236:237], v[38:39]
	v_lshlrev_b32_e32 v236, 16, v136
	v_and_b32_e32 v237, 0xffff0000, v136
	v_pk_fma_f32 v[228:229], v[68:69], v[236:237], v[228:229]
	v_lshlrev_b32_e32 v236, 16, v137
	v_and_b32_e32 v237, 0xffff0000, v137
	v_pk_fma_f32 v[230:231], v[70:71], v[236:237], v[230:231]
	v_lshlrev_b32_e32 v236, 16, v138
	v_and_b32_e32 v237, 0xffff0000, v138
	v_pk_fma_f32 v[232:233], v[52:53], v[236:237], v[232:233]
	v_lshlrev_b32_e32 v236, 16, v139
	v_and_b32_e32 v237, 0xffff0000, v139
	v_pk_fma_f32 v[234:235], v[54:55], v[236:237], v[234:235]
	v_lshlrev_b32_e32 v236, 16, v140
	v_and_b32_e32 v237, 0xffff0000, v140
	v_pk_fma_f32 v[228:229], v[60:61], v[236:237], v[228:229]
	v_lshlrev_b32_e32 v236, 16, v141
	v_and_b32_e32 v237, 0xffff0000, v141
	v_pk_fma_f32 v[230:231], v[62:63], v[236:237], v[230:231]
	v_lshlrev_b32_e32 v236, 16, v142
	v_and_b32_e32 v237, 0xffff0000, v142
	v_pk_fma_f32 v[232:233], v[56:57], v[236:237], v[232:233]
	v_lshlrev_b32_e32 v236, 16, v143
	v_and_b32_e32 v237, 0xffff0000, v143
	v_pk_fma_f32 v[234:235], v[58:59], v[236:237], v[234:235]
	v_lshlrev_b32_e32 v236, 16, v96
	v_and_b32_e32 v237, 0xffff0000, v96
	v_pk_fma_f32 v[228:229], v[64:65], v[236:237], v[228:229]
	v_lshlrev_b32_e32 v236, 16, v97
	v_and_b32_e32 v237, 0xffff0000, v97
	v_pk_fma_f32 v[230:231], v[66:67], v[236:237], v[230:231]
	v_lshlrev_b32_e32 v236, 16, v98
	v_and_b32_e32 v237, 0xffff0000, v98
	v_pk_fma_f32 v[232:233], v[72:73], v[236:237], v[232:233]
	v_lshlrev_b32_e32 v236, 16, v99
	v_and_b32_e32 v237, 0xffff0000, v99
	v_pk_fma_f32 v[234:235], v[74:75], v[236:237], v[234:235]
	v_cvt_pk_bf16_f32 v240, v228, v229
	v_cvt_pk_bf16_f32 v241, v230, v231
	v_cvt_pk_bf16_f32 v242, v232, v233
	v_cvt_pk_bf16_f32 v243, v234, v235
	ds_write_b128 v93, v[240:243] offset:8704
	s_add_i32 s4, s4, 64
	v_add_u32_e32 v93, 0x4400, v93
	s_cmpk_eq_i32 s4, 0x100
	s_cbranch_scc0 .LBB0_1034
	s_branch .LBB0_1050

.LBB0_1296:
	v_add_u32_e32 v216, s3, v177
	v_and_b32_e32 v217, 63, v216
	v_xor_b32_e32 v227, 32, v217
	v_add_u32_e32 v244, s3, v86
	v_add_u32_e32 v244, -1, v244
	v_ashrrev_i32_e32 v245, 31, v244
	v_lshlrev_b64 v[244:245], 12, v[244:245]
	v_lshl_add_u64 v[208:209], v[162:163], 0, v[244:245]
	s_mov_b32 s0, 0x2000
	s_mov_b32 s1, 0
	v_lshl_add_u64 v[210:211], v[208:209], 0, s[0:1]
	s_mov_b32 s0, 0x20000
	v_lshl_add_u64 v[212:213], v[208:209], 0, s[0:1]
	v_lshl_add_u64 v[214:215], v[210:211], 0, s[0:1]
	v_mov_b32_e32 v88, 0
	v_mov_b32_e32 v89, 0
	v_mov_b32_e32 v90, 0
	v_mov_b32_e32 v91, 0
	v_mov_b32_e32 v92, 0
	v_mov_b32_e32 v93, 0
	v_mov_b32_e32 v94, 0
	v_mov_b32_e32 v95, 0
	v_mov_b32_e32 v100, 0
	v_mov_b32_e32 v101, 0
	v_mov_b32_e32 v102, 0
	v_mov_b32_e32 v103, 0
	v_mov_b32_e32 v104, 0
	v_mov_b32_e32 v105, 0
	v_mov_b32_e32 v106, 0
	v_mov_b32_e32 v107, 0
	v_mov_b32_e32 v108, 0
	v_mov_b32_e32 v109, 0
	v_mov_b32_e32 v110, 0
	v_mov_b32_e32 v111, 0
	v_mov_b32_e32 v116, 0
	v_mov_b32_e32 v117, 0
	v_mov_b32_e32 v118, 0
	v_mov_b32_e32 v119, 0
	s_movk_i32 s1, 63
	v_cmp_lt_u32_e64 s[12:13], 1, v217
	v_cmp_lt_u32_e64 s[14:15], 0, v217
	v_cmp_gt_u32_e64 s[20:21], s1, v217
	s_mov_b64 exec, s[12:13]
	global_load_dwordx4 v[88:91], v[208:209], off offset:-4096
	s_mov_b64 exec, s[14:15]
	global_load_dwordx4 v[92:95], v[208:209], off
	s_mov_b64 exec, -1
	global_load_dwordx4 v[96:99], v[210:211], off offset:-4096
	s_mov_b64 exec, s[20:21]
	global_load_dwordx4 v[100:103], v[210:211], off
	s_mov_b64 exec, -1
	v_cmp_lt_u32_e64 s[12:13], 1, v227
	v_cmp_lt_u32_e64 s[14:15], 0, v227
	v_cmp_gt_u32_e64 s[20:21], s1, v227
	s_mov_b64 exec, s[12:13]
	global_load_dwordx4 v[104:107], v[212:213], off offset:-4096
	s_mov_b64 exec, s[14:15]
	global_load_dwordx4 v[108:111], v[212:213], off
	s_mov_b64 exec, -1
	global_load_dwordx4 v[112:115], v[214:215], off offset:-4096
	s_mov_b64 exec, s[20:21]
	global_load_dwordx4 v[116:119], v[214:215], off
	s_mov_b64 exec, -1
	s_waitcnt vmcnt(0)
	v_lshlrev_b32_e32 v236, 16, v88
	v_and_b32_e32 v237, 0xffff0000, v88
	v_pk_fma_f32 v[228:229], v[48:49], v[236:237], v[40:41]
	v_lshlrev_b32_e32 v236, 16, v89
	v_and_b32_e32 v237, 0xffff0000, v89
	v_pk_fma_f32 v[230:231], v[50:51], v[236:237], v[42:43]
	v_lshlrev_b32_e32 v236, 16, v90
	v_and_b32_e32 v237, 0xffff0000, v90
	v_pk_fma_f32 v[232:233], v[44:45], v[236:237], v[36:37]
	v_lshlrev_b32_e32 v236, 16, v91
	v_and_b32_e32 v237, 0xffff0000, v91
	v_pk_fma_f32 v[234:235], v[46:47], v[236:237], v[38:39]
	v_lshlrev_b32_e32 v236, 16, v92
	v_and_b32_e32 v237, 0xffff0000, v92
	v_pk_fma_f32 v[228:229], v[68:69], v[236:237], v[228:229]
	v_lshlrev_b32_e32 v236, 16, v93
	v_and_b32_e32 v237, 0xffff0000, v93
	v_pk_fma_f32 v[230:231], v[70:71], v[236:237], v[230:231]
	v_lshlrev_b32_e32 v236, 16, v94
	v_and_b32_e32 v237, 0xffff0000, v94
	v_pk_fma_f32 v[232:233], v[52:53], v[236:237], v[232:233]
	v_lshlrev_b32_e32 v236, 16, v95
	v_and_b32_e32 v237, 0xffff0000, v95
	v_pk_fma_f32 v[234:235], v[54:55], v[236:237], v[234:235]
	v_lshlrev_b32_e32 v236, 16, v96
	v_and_b32_e32 v237, 0xffff0000, v96
	v_pk_fma_f32 v[228:229], v[60:61], v[236:237], v[228:229]
	v_lshlrev_b32_e32 v236, 16, v97
	v_and_b32_e32 v237, 0xffff0000, v97
	v_pk_fma_f32 v[230:231], v[62:63], v[236:237], v[230:231]
	v_lshlrev_b32_e32 v236, 16, v98
	v_and_b32_e32 v237, 0xffff0000, v98
	v_pk_fma_f32 v[232:233], v[56:57], v[236:237], v[232:233]
	v_lshlrev_b32_e32 v236, 16, v99
	v_and_b32_e32 v237, 0xffff0000, v99
	v_pk_fma_f32 v[234:235], v[58:59], v[236:237], v[234:235]
	v_lshlrev_b32_e32 v236, 16, v100
	v_and_b32_e32 v237, 0xffff0000, v100
	v_pk_fma_f32 v[228:229], v[64:65], v[236:237], v[228:229]
	v_lshlrev_b32_e32 v236, 16, v101
	v_and_b32_e32 v237, 0xffff0000, v101
	v_pk_fma_f32 v[230:231], v[66:67], v[236:237], v[230:231]
	v_lshlrev_b32_e32 v236, 16, v102
	v_and_b32_e32 v237, 0xffff0000, v102
	v_pk_fma_f32 v[232:233], v[72:73], v[236:237], v[232:233]
	v_lshlrev_b32_e32 v236, 16, v103
	v_and_b32_e32 v237, 0xffff0000, v103
	v_pk_fma_f32 v[234:235], v[74:75], v[236:237], v[234:235]
	v_cvt_pk_bf16_f32 v240, v228, v229
	v_cvt_pk_bf16_f32 v241, v230, v231
	v_cvt_pk_bf16_f32 v242, v232, v233
	v_cvt_pk_bf16_f32 v243, v234, v235
	ds_write_b128 v87, v[240:243]
	v_lshlrev_b32_e32 v236, 16, v104
	v_and_b32_e32 v237, 0xffff0000, v104
	v_pk_fma_f32 v[228:229], v[48:49], v[236:237], v[40:41]
	v_lshlrev_b32_e32 v236, 16, v105
	v_and_b32_e32 v237, 0xffff0000, v105
	v_pk_fma_f32 v[230:231], v[50:51], v[236:237], v[42:43]
	v_lshlrev_b32_e32 v236, 16, v106
	v_and_b32_e32 v237, 0xffff0000, v106
	v_pk_fma_f32 v[232:233], v[44:45], v[236:237], v[36:37]
	v_lshlrev_b32_e32 v236, 16, v107
	v_and_b32_e32 v237, 0xffff0000, v107
	v_pk_fma_f32 v[234:235], v[46:47], v[236:237], v[38:39]
	v_lshlrev_b32_e32 v236, 16, v108
	v_and_b32_e32 v237, 0xffff0000, v108
	v_pk_fma_f32 v[228:229], v[68:69], v[236:237], v[228:229]
	v_lshlrev_b32_e32 v236, 16, v109
	v_and_b32_e32 v237, 0xffff0000, v109
	v_pk_fma_f32 v[230:231], v[70:71], v[236:237], v[230:231]
	v_lshlrev_b32_e32 v236, 16, v110
	v_and_b32_e32 v237, 0xffff0000, v110
	v_pk_fma_f32 v[232:233], v[52:53], v[236:237], v[232:233]
	v_lshlrev_b32_e32 v236, 16, v111
	v_and_b32_e32 v237, 0xffff0000, v111
	v_pk_fma_f32 v[234:235], v[54:55], v[236:237], v[234:235]
	v_lshlrev_b32_e32 v236, 16, v112
	v_and_b32_e32 v237, 0xffff0000, v112
	v_pk_fma_f32 v[228:229], v[60:61], v[236:237], v[228:229]
	v_lshlrev_b32_e32 v236, 16, v113
	v_and_b32_e32 v237, 0xffff0000, v113
	v_pk_fma_f32 v[230:231], v[62:63], v[236:237], v[230:231]
	v_lshlrev_b32_e32 v236, 16, v114
	v_and_b32_e32 v237, 0xffff0000, v114
	v_pk_fma_f32 v[232:233], v[56:57], v[236:237], v[232:233]
	v_lshlrev_b32_e32 v236, 16, v115
	v_and_b32_e32 v237, 0xffff0000, v115
	v_pk_fma_f32 v[234:235], v[58:59], v[236:237], v[234:235]
	v_lshlrev_b32_e32 v236, 16, v116
	v_and_b32_e32 v237, 0xffff0000, v116
	v_pk_fma_f32 v[228:229], v[64:65], v[236:237], v[228:229]
	v_lshlrev_b32_e32 v236, 16, v117
	v_and_b32_e32 v237, 0xffff0000, v117
	v_pk_fma_f32 v[230:231], v[66:67], v[236:237], v[230:231]
	v_lshlrev_b32_e32 v236, 16, v118
	v_and_b32_e32 v237, 0xffff0000, v118
	v_pk_fma_f32 v[232:233], v[72:73], v[236:237], v[232:233]
	v_lshlrev_b32_e32 v236, 16, v119
	v_and_b32_e32 v237, 0xffff0000, v119
	v_pk_fma_f32 v[234:235], v[74:75], v[236:237], v[234:235]
	v_cvt_pk_bf16_f32 v240, v228, v229
	v_cvt_pk_bf16_f32 v241, v230, v231
	v_cvt_pk_bf16_f32 v242, v232, v233
	v_cvt_pk_bf16_f32 v243, v234, v235
	ds_write_b128 v87, v[240:243] offset:8704
	s_add_i32 s3, s3, 64
	v_add_u32_e32 v87, 0x4400, v87
	s_cmpk_eq_i32 s3, 0x100
	s_cbranch_scc0 .LBB0_1296
	s_branch .LBB0_1375
